# w_ple_gate conversion moved from phase 3 into the idle tail of phase 7 (pipelined loop)
# speedup vs baseline: 1.0148x; 1.0006x over previous
; __device__ __forceinline__ void convert_items(const Params& p, LAS float* scr, int lane, int gw, int NGW, int it_lo, int it_hi) {
;     unsigned char* ws = p.ws;
;     for (int it = it_lo + gw; it < it_hi; it += NGW) {
;         int r = it;
;         if (r < CV_WIN) { const int kb = r / 417, nb = r % 417, ns = nb * 32; const int nd = ns < 9216 ? ns : (ns < 9248 ? 13312 + (ns - 9216) : ns - 32);
;             transpose_item(p.in[8], IN_COLS, 2048, (bf16_t*)(ws + WS_WIN), kb * 64, ns, nd, scr, lane); continue; } r -= CV_WIN;
;         if (r < CV_POOL) { const int g = r / 32, q = r % 32, kb = q / 8, nb = q % 8;
;             transpose_item(p.in[9] + g * 65536, 256, 256, (bf16_t*)(ws + WS_WPOOL) + g * 65536, kb * 64, nb * 32, nb * 32, scr, lane); continue; } r -= CV_POOL;
;         if (r < CV_WPU) { const int kb = r / 64, nb = r % 64; transpose_item(p.in[15], 2048, 1024, (bf16_t*)(ws + WS_WPU), kb * 64, nb * 32, nb * 32, scr, lane); continue; } r -= CV_WPU;
;         if (r < CV_2K) { const int kb = r / 64, nb = r % 64; transpose_item(p.in[16], 2048, 2048, (bf16_t*)(ws + WS_WGU), kb * 64, nb * 32, nb * 32, scr, lane); continue; } r -= CV_2K;
;         if (r < CV_2K) { const int kb = r / 64, nb = r % 64; transpose_item(p.in[17], 2048, 2048, (bf16_t*)(ws + WS_WO), kb * 64, nb * 32, nb * 32, scr, lane); continue; } r -= CV_2K;
;         if (r < CV_GATE) { const int kb = r / 352, nb = r % 352, ns = nb * 32; int nd; if (ns < DFF) nd = 256 * (ns / 128) + (ns % 128); else { const int j = ns - DFF; nd = 256 * (j / 128) + 128 + (j % 128); }
;             transpose_item(p.in[19], 2 * DFF, 2048, (bf16_t*)(ws + WS_WGATE), kb * 64, ns, nd, scr, lane); continue; } r -= CV_GATE;
;         if (r < CV_2K) { const int kb = r / 64, nb = r % 64; transpose_item(p.in[22], 2048, 2048, (bf16_t*)(ws + WS_WPLEG), kb * 64, nb * 32, nb * 32, scr, lane); continue; } r -= CV_2K;
;         if (r < CV_DOWN) { const int kb = r / 64, nb = r % 64; transpose_item(p.in[20], 2048, DFF, (bf16_t*)(ws + WS_WDOWN), kb * 64, nb * 32, nb * 32, scr, lane); continue; } r -= CV_DOWN;
;         { const int kb = r / 64, nb = r % 64; transpose_item(p.in[21], 2048, 256, (bf16_t*)(ws + WS_WPLE), kb * 64, nb * 32, nb * 32, scr, lane); }
;     }
; }
; __global__ void __launch_bounds__(512, 2) mega(Params p) {
;     ...
;             { const int tid = opaque_tid(wave_s), lane = tid & 63, wave = tid >> 6;
.LBB0_857:
	s_mov_b32 s0, 0
	s_nop 0
	v_mbcnt_lo_u32_b32 v0, -1, s0
	v_mbcnt_hi_u32_b32 v0, -1, v0
	v_or_b32_e32 v0, s24, v0
	s_movk_i32 s0, 0x1700
	v_ashrrev_i32_e32 v1, 6, v0
	v_lshl_add_u32 v2, s14, 3, v1
	v_cmp_gt_i32_e32 vcc, s0, v2
	s_and_saveexec_b64 s[0:1], vcc
	s_cbranch_execz .LBB0_896
	s_movk_i32 s6, 0x2100
	v_bfe_u32 v41, v0, 5, 1
	v_and_b32_e32 v34, 31, v0
	v_bfe_u32 v43, v0, 3, 3
	v_lshlrev_b32_e32 v0, 3, v0
	v_mul_lo_u32 v1, v1, s6
	v_and_b32_e32 v36, 56, v0
	v_add_u32_e32 v4, 0, v1
	v_mov_b32_e32 v1, 0
	v_lshlrev_b32_e32 v0, 1, v36
	v_add_u32_e32 v40, 0x7ca0, v2
	v_lshlrev_b32_e32 v32, 2, v34
	v_mul_u32_u24_e32 v2, 0x84, v41
	v_lshl_add_u64 v[14:15], s[22:23], 0, v[0:1]
	s_mov_b64 s[6:7], 0x5680000
	v_add3_u32 v42, v4, v32, v2
	v_mul_u32_u24_e32 v5, 0x84, v36
	v_lshl_add_u64 v[2:3], v[14:15], 0, s[6:7]
	v_lshlrev_b32_e32 v6, 2, v43
	s_mov_b64 s[6:7], 0x4080000
	v_add3_u32 v44, v4, v5, v6
	v_lshl_add_u64 v[4:5], v[14:15], 0, s[6:7]
	s_mov_b64 s[6:7], 0x5780000
	v_lshl_add_u64 v[6:7], v[14:15], 0, s[6:7]
	s_mov_b64 s[6:7], 0x1480000
	v_lshl_add_u64 v[8:9], v[14:15], 0, s[6:7]
	s_mov_b64 s[6:7], 0xc80000
	v_lshl_add_u64 v[10:11], v[14:15], 0, s[6:7]
	s_mov_b64 s[6:7], 0x480000
	v_readlane_b32 s36, v254, 0
	v_lshl_add_u64 v[12:13], v[14:15], 0, s[6:7]
	s_mov_b64 s[6:7], 0x80000
	v_mov_b32_e32 v33, v1
	v_readlane_b32 s37, v254, 1
	v_readlane_b32 s38, v254, 2
	v_readlane_b32 s39, v254, 3
	v_readlane_b32 s40, v254, 4
	v_readlane_b32 s41, v254, 5
	v_readlane_b32 s42, v254, 6
	v_readlane_b32 s43, v254, 7
	v_readlane_b32 s44, v254, 8
	v_readlane_b32 s45, v254, 9
	v_readlane_b32 s46, v254, 10
	v_readlane_b32 s47, v254, 11
	v_readlane_b32 s48, v254, 12
	v_readlane_b32 s49, v254, 13
	v_readlane_b32 s50, v254, 14
	v_readlane_b32 s51, v254, 15
	s_lshl_b32 s3, s12, 3
	v_or_b32_e32 v45, 8, v43
	v_or_b32_e32 v46, 16, v43
	v_or_b32_e32 v47, 24, v43
	v_lshl_add_u64 v[14:15], v[14:15], 0, s[6:7]
	v_lshl_add_u64 v[16:17], s[4:5], 0, v[0:1]
	v_lshl_add_u64 v[18:19], s[46:47], 0, v[32:33]
	v_lshl_add_u64 v[20:21], s[44:45], 0, v[32:33]
	v_lshl_add_u64 v[22:23], s[48:49], 0, v[32:33]
	v_lshl_add_u64 v[24:25], s[42:43], 0, v[32:33]
	v_lshl_add_u64 v[26:27], s[38:39], 0, v[32:33]
	v_lshl_add_u64 v[28:29], s[36:37], 0, v[32:33]
	v_lshl_add_u64 v[30:31], s[82:83], 0, v[32:33]
	v_lshl_add_u64 v[32:33], s[68:69], 0, v[32:33]
	v_lshlrev_b32_e32 v48, 5, v40
	s_lshl_b32 s25, s12, 8
	v_lshlrev_b32_e32 v49, 11, v40
	s_lshl_b32 s34, s12, 14
	v_lshlrev_b32_e32 v50, 3, v40
	s_lshl_b32 s35, s12, 6
	s_mov_b64 s[4:5], 0
	s_movk_i32 s36, 0x341f
	s_movk_i32 s37, 0x349f
	s_movk_i32 s38, 0x389f
	s_movk_i32 s39, 0x409f
	s_movk_i32 s40, 0x489f
	s_movk_i32 s41, 0x749f
	s_movk_i32 s42, 0x7c9f
	s_mov_b32 s43, 0x929f
	s_movk_i32 s44, 0x160
	s_movk_i32 s45, 0xaf
	s_movk_i32 s46, 0x80
	s_movk_i32 s47, 0x3f00
	v_lshlrev_b32_e32 v34, 2, v34
	s_movk_i32 s48, 0x1000
	s_movk_i32 s49, 0x2000
	s_movk_i32 s50, 0x3000
	s_movk_i32 s51, 0x4000
	s_movk_i32 s56, 0x5000
	s_movk_i32 s57, 0x6000
	s_movk_i32 s58, 0x7000
	s_mov_b32 s59, 0x8000
	s_mov_b32 s60, 0x9000
	s_mov_b32 s61, 0xa000
	s_mov_b32 s62, 0xb000
	s_mov_b32 s63, 0xc000
	s_mov_b32 s64, 0xd000
	s_mov_b32 s65, 0xe000
	s_mov_b32 s66, 0xf000
	v_lshlrev_b32_e32 v36, 1, v36
	s_mov_b32 s67, 0x274a4871
	s_movk_i32 s68, 0x120
	s_mov_b32 s69, 0xd080
	s_mov_b32 s72, 0x939f
	v_mov_b32_e32 v51, 6
	v_mov_b32_e32 v52, 0x3400
	s_branch .LBB0_860

; #define LAS __attribute__((address_space(3)))
; __device__ __forceinline__ unsigned pk2(float lo, float hi) { const f32x2_t v = {lo, hi}; const bf16x2_t b = __builtin_convertvector(v, bf16x2_t); return __builtin_bit_cast(unsigned, b); }
; #define LDS_WAIT() asm volatile("s_waitcnt lgkmcnt(0)" ::: "memory")
; __device__ __forceinline__ void transpose_item(const float* W, int N, int K, bf16_t* WT, int k0, int n0src, int n0dst, LAS float* scr, int lane) {
;     float tv[32];
; #pragma unroll
;     for (int i = 0; i < 32; ++i) tv[i] = __builtin_nontemporal_load(&W[(size_t)(k0 + 2 * i + (lane >> 5)) * N + n0src + (lane & 31)]);
; #pragma unroll
;     for (int i = 0; i < 32; ++i) scr[(2 * i + (lane >> 5)) * 33 + (lane & 31)] = tv[i];
;     LDS_WAIT();
;     const int c = lane & 7;
; #pragma unroll
;     for (int j = 0; j < 4; ++j) { const int n = (lane >> 3) + 8 * j; const LAS float* s = scr + (8 * c) * 33 + n;
;         u32x4 o; o.x = pk2(s[0 * 33], s[1 * 33]); o.y = pk2(s[2 * 33], s[3 * 33]); o.z = pk2(s[4 * 33], s[5 * 33]); o.w = pk2(s[6 * 33], s[7 * 33]);
;         *(u32x4*)(WT + (size_t)(n0dst + n) * K + k0 + 8 * c) = o; }
;     LDS_WAIT();
; }
; __device__ __forceinline__ void convert_items(const Params& p, LAS float* scr, int lane, int gw, int NGW, int it_lo, int it_hi) {
;     ...
;         if (r < CV_2K) { const int kb = r / 64, nb = r % 64; transpose_item(p.in[22], 2048, 2048, (bf16_t*)(ws + WS_WPLEG), kb * 64, nb * 32, nb * 32, scr, lane); continue; } r -= CV_2K;
.Lp9a_1354:
	v_readlane_b32 s2, v254, 36
	v_readlane_b32 s33, v254, 37
	s_nop 4
	s_cmp_lt_u32 s2, 0xb0
	s_cbranch_scc1 .Lp7t_pleg_done
	s_mov_b64 exec, -1
	v_mbcnt_lo_u32_b32 v0, -1, 0
	v_mbcnt_hi_u32_b32 v0, -1, v0
	s_lshr_b32 s84, s24, 6
	s_sub_i32 s85, s2, 0xb0
	s_lshl_b32 s85, s85, 3
	s_add_i32 s85, s85, s84
	v_readlane_b32 s86, v254, 12
	v_readlane_b32 s87, v254, 13
	s_mul_i32 s90, s84, 0x2100
	v_lshrrev_b32_e32 v1, 5, v0
	v_and_b32_e32 v2, 31, v0
	v_mul_u32_u24_e32 v3, 0x2000, v1
	v_lshl_add_u32 v3, v2, 2, v3
	v_mul_u32_u24_e32 v4, 33, v1
	v_add_u32_e32 v4, v4, v2
	v_lshl_add_u32 v4, v4, 2, s90
	v_and_b32_e32 v5, 7, v0
	v_lshrrev_b32_e32 v6, 3, v0
	v_mul_u32_u24_e32 v7, 0x420, v5
	v_lshl_add_u32 v7, v6, 2, v7
	v_add_u32_e32 v7, s90, v7
	v_mul_u32_u24_e32 v8, 0x1000, v6
	v_lshl_add_u32 v8, v5, 4, v8
	v_add_u32_e32 v9, 0x8000, v8
	v_add_u32_e32 v10, 0x10000, v8
	v_add_u32_e32 v11, 0x18000, v8
	s_cmp_lt_u32 s85, 0x800
	s_cbranch_scc0 .Lp7t_pleg_done
	s_lshr_b32 s91, s85, 6
	s_mul_i32 s92, s91, 0x40
	s_sub_i32 s92, s85, s92
	s_lshl_b32 s92, s92, 5
	s_mov_b32 s95, s92
	s_mul_i32 s96, s91, 0x80000
	s_lshl_b32 s97, s92, 2
	s_add_i32 s96, s96, s97
	s_add_u32 s96, s86, s96
	s_addc_u32 s97, s87, 0
	global_load_dword v16, v3, s[96:97] nt
	s_add_u32 s96, s96, 0x4000
	s_addc_u32 s97, s97, 0
	global_load_dword v17, v3, s[96:97] nt
	s_add_u32 s96, s96, 0x4000
	s_addc_u32 s97, s97, 0
	global_load_dword v18, v3, s[96:97] nt
	s_add_u32 s96, s96, 0x4000
	s_addc_u32 s97, s97, 0
	global_load_dword v19, v3, s[96:97] nt
	s_add_u32 s96, s96, 0x4000
	s_addc_u32 s97, s97, 0
	global_load_dword v20, v3, s[96:97] nt
	s_add_u32 s96, s96, 0x4000
	s_addc_u32 s97, s97, 0
	global_load_dword v21, v3, s[96:97] nt
	s_add_u32 s96, s96, 0x4000
	s_addc_u32 s97, s97, 0
	global_load_dword v22, v3, s[96:97] nt
	s_add_u32 s96, s96, 0x4000
	s_addc_u32 s97, s97, 0
	global_load_dword v23, v3, s[96:97] nt
	s_add_u32 s96, s96, 0x4000
	s_addc_u32 s97, s97, 0
	global_load_dword v24, v3, s[96:97] nt
	s_add_u32 s96, s96, 0x4000
	s_addc_u32 s97, s97, 0
	global_load_dword v25, v3, s[96:97] nt
	s_add_u32 s96, s96, 0x4000
	s_addc_u32 s97, s97, 0
	global_load_dword v26, v3, s[96:97] nt
	s_add_u32 s96, s96, 0x4000
	s_addc_u32 s97, s97, 0
	global_load_dword v27, v3, s[96:97] nt
	s_add_u32 s96, s96, 0x4000
	s_addc_u32 s97, s97, 0
	global_load_dword v28, v3, s[96:97] nt
	s_add_u32 s96, s96, 0x4000
	s_addc_u32 s97, s97, 0
	global_load_dword v29, v3, s[96:97] nt
	s_add_u32 s96, s96, 0x4000
	s_addc_u32 s97, s97, 0
	global_load_dword v30, v3, s[96:97] nt
	s_add_u32 s96, s96, 0x4000
	s_addc_u32 s97, s97, 0
	global_load_dword v31, v3, s[96:97] nt
	s_add_u32 s96, s96, 0x4000
	s_addc_u32 s97, s97, 0
	global_load_dword v32, v3, s[96:97] nt
	s_add_u32 s96, s96, 0x4000
	s_addc_u32 s97, s97, 0
	global_load_dword v33, v3, s[96:97] nt
	s_add_u32 s96, s96, 0x4000
	s_addc_u32 s97, s97, 0
	global_load_dword v34, v3, s[96:97] nt
	s_add_u32 s96, s96, 0x4000
	s_addc_u32 s97, s97, 0
	global_load_dword v35, v3, s[96:97] nt
	s_add_u32 s96, s96, 0x4000
	s_addc_u32 s97, s97, 0
	global_load_dword v36, v3, s[96:97] nt
	s_add_u32 s96, s96, 0x4000
	s_addc_u32 s97, s97, 0
	global_load_dword v37, v3, s[96:97] nt
	s_add_u32 s96, s96, 0x4000
	s_addc_u32 s97, s97, 0
	global_load_dword v38, v3, s[96:97] nt
	s_add_u32 s96, s96, 0x4000
	s_addc_u32 s97, s97, 0
	global_load_dword v39, v3, s[96:97] nt
	s_add_u32 s96, s96, 0x4000
	s_addc_u32 s97, s97, 0
	global_load_dword v40, v3, s[96:97] nt
	s_add_u32 s96, s96, 0x4000
	s_addc_u32 s97, s97, 0
	global_load_dword v41, v3, s[96:97] nt
	s_add_u32 s96, s96, 0x4000
	s_addc_u32 s97, s97, 0
	global_load_dword v42, v3, s[96:97] nt
	s_add_u32 s96, s96, 0x4000
	s_addc_u32 s97, s97, 0
	global_load_dword v43, v3, s[96:97] nt
	s_add_u32 s96, s96, 0x4000
	s_addc_u32 s97, s97, 0
	global_load_dword v44, v3, s[96:97] nt
	s_add_u32 s96, s96, 0x4000
	s_addc_u32 s97, s97, 0
	global_load_dword v45, v3, s[96:97] nt
	s_add_u32 s96, s96, 0x4000
	s_addc_u32 s97, s97, 0
	global_load_dword v46, v3, s[96:97] nt
	s_add_u32 s96, s96, 0x4000
	s_addc_u32 s97, s97, 0
	global_load_dword v47, v3, s[96:97] nt
	s_mul_i32 s92, s95, 0x1000
	s_lshl_b32 s93, s91, 7
	s_add_i32 s92, s92, s93
	s_add_u32 s100, s22, s92
	s_addc_u32 s101, s23, 0
	s_add_u32 s100, s100, 0x5780000
	s_addc_u32 s101, s101, 0
; #define LAS __attribute__((address_space(3)))
; __device__ __forceinline__ unsigned pk2(float lo, float hi) { const f32x2_t v = {lo, hi}; const bf16x2_t b = __builtin_convertvector(v, bf16x2_t); return __builtin_bit_cast(unsigned, b); }
; #define LDS_WAIT() asm volatile("s_waitcnt lgkmcnt(0)" ::: "memory")
; __device__ __forceinline__ void transpose_item(const float* W, int N, int K, bf16_t* WT, int k0, int n0src, int n0dst, LAS float* scr, int lane) {
;     float tv[32];
; #pragma unroll
;     for (int i = 0; i < 32; ++i) tv[i] = __builtin_nontemporal_load(&W[(size_t)(k0 + 2 * i + (lane >> 5)) * N + n0src + (lane & 31)]);
; #pragma unroll
;     for (int i = 0; i < 32; ++i) scr[(2 * i + (lane >> 5)) * 33 + (lane & 31)] = tv[i];
;     LDS_WAIT();
;     const int c = lane & 7;
; #pragma unroll
;     for (int j = 0; j < 4; ++j) { const int n = (lane >> 3) + 8 * j; const LAS float* s = scr + (8 * c) * 33 + n;
;         u32x4 o; o.x = pk2(s[0 * 33], s[1 * 33]); o.y = pk2(s[2 * 33], s[3 * 33]); o.z = pk2(s[4 * 33], s[5 * 33]); o.w = pk2(s[6 * 33], s[7 * 33]);
;         *(u32x4*)(WT + (size_t)(n0dst + n) * K + k0 + 8 * c) = o; }
;     LDS_WAIT();
; }
.Lp7t_pleg_loop:
	s_add_i32 s85, s85, 0x280
	s_cmp_lt_u32 s85, 0x800
	s_cbranch_scc0 .Lp7t_pleg_lastA
	s_lshr_b32 s91, s85, 6
	s_mul_i32 s92, s91, 0x40
	s_sub_i32 s92, s85, s92
	s_lshl_b32 s92, s92, 5
	s_mov_b32 s95, s92
	s_mul_i32 s96, s91, 0x80000
	s_lshl_b32 s97, s92, 2
	s_add_i32 s96, s96, s97
	s_add_u32 s96, s86, s96
	s_addc_u32 s97, s87, 0
	global_load_dword v96, v3, s[96:97] nt
	s_add_u32 s96, s96, 0x4000
	s_addc_u32 s97, s97, 0
	global_load_dword v97, v3, s[96:97] nt
	s_add_u32 s96, s96, 0x4000
	s_addc_u32 s97, s97, 0
	global_load_dword v98, v3, s[96:97] nt
	s_add_u32 s96, s96, 0x4000
	s_addc_u32 s97, s97, 0
	global_load_dword v99, v3, s[96:97] nt
	s_add_u32 s96, s96, 0x4000
	s_addc_u32 s97, s97, 0
	global_load_dword v100, v3, s[96:97] nt
	s_add_u32 s96, s96, 0x4000
	s_addc_u32 s97, s97, 0
	global_load_dword v101, v3, s[96:97] nt
	s_add_u32 s96, s96, 0x4000
	s_addc_u32 s97, s97, 0
	global_load_dword v102, v3, s[96:97] nt
	s_add_u32 s96, s96, 0x4000
	s_addc_u32 s97, s97, 0
	global_load_dword v103, v3, s[96:97] nt
	s_add_u32 s96, s96, 0x4000
	s_addc_u32 s97, s97, 0
	global_load_dword v104, v3, s[96:97] nt
	s_add_u32 s96, s96, 0x4000
	s_addc_u32 s97, s97, 0
	global_load_dword v105, v3, s[96:97] nt
	s_add_u32 s96, s96, 0x4000
	s_addc_u32 s97, s97, 0
	global_load_dword v106, v3, s[96:97] nt
	s_add_u32 s96, s96, 0x4000
	s_addc_u32 s97, s97, 0
	global_load_dword v107, v3, s[96:97] nt
	s_add_u32 s96, s96, 0x4000
	s_addc_u32 s97, s97, 0
	global_load_dword v108, v3, s[96:97] nt
	s_add_u32 s96, s96, 0x4000
	s_addc_u32 s97, s97, 0
	global_load_dword v109, v3, s[96:97] nt
	s_add_u32 s96, s96, 0x4000
	s_addc_u32 s97, s97, 0
	global_load_dword v110, v3, s[96:97] nt
	s_add_u32 s96, s96, 0x4000
	s_addc_u32 s97, s97, 0
	global_load_dword v111, v3, s[96:97] nt
	s_add_u32 s96, s96, 0x4000
	s_addc_u32 s97, s97, 0
	global_load_dword v112, v3, s[96:97] nt
	s_add_u32 s96, s96, 0x4000
	s_addc_u32 s97, s97, 0
	global_load_dword v113, v3, s[96:97] nt
	s_add_u32 s96, s96, 0x4000
	s_addc_u32 s97, s97, 0
	global_load_dword v114, v3, s[96:97] nt
	s_add_u32 s96, s96, 0x4000
	s_addc_u32 s97, s97, 0
	global_load_dword v115, v3, s[96:97] nt
	s_add_u32 s96, s96, 0x4000
	s_addc_u32 s97, s97, 0
	global_load_dword v116, v3, s[96:97] nt
	s_add_u32 s96, s96, 0x4000
	s_addc_u32 s97, s97, 0
	global_load_dword v117, v3, s[96:97] nt
	s_add_u32 s96, s96, 0x4000
	s_addc_u32 s97, s97, 0
	global_load_dword v118, v3, s[96:97] nt
	s_add_u32 s96, s96, 0x4000
	s_addc_u32 s97, s97, 0
	global_load_dword v119, v3, s[96:97] nt
	s_add_u32 s96, s96, 0x4000
	s_addc_u32 s97, s97, 0
	global_load_dword v120, v3, s[96:97] nt
	s_add_u32 s96, s96, 0x4000
	s_addc_u32 s97, s97, 0
	global_load_dword v121, v3, s[96:97] nt
	s_add_u32 s96, s96, 0x4000
	s_addc_u32 s97, s97, 0
	global_load_dword v122, v3, s[96:97] nt
	s_add_u32 s96, s96, 0x4000
	s_addc_u32 s97, s97, 0
	global_load_dword v123, v3, s[96:97] nt
	s_add_u32 s96, s96, 0x4000
	s_addc_u32 s97, s97, 0
	global_load_dword v124, v3, s[96:97] nt
	s_add_u32 s96, s96, 0x4000
	s_addc_u32 s97, s97, 0
	global_load_dword v125, v3, s[96:97] nt
	s_add_u32 s96, s96, 0x4000
	s_addc_u32 s97, s97, 0
	global_load_dword v126, v3, s[96:97] nt
	s_add_u32 s96, s96, 0x4000
	s_addc_u32 s97, s97, 0
	global_load_dword v127, v3, s[96:97] nt
	s_mul_i32 s92, s95, 0x1000
	s_lshl_b32 s93, s91, 7
	s_add_i32 s92, s92, s93
	s_add_u32 s98, s22, s92
	s_addc_u32 s99, s23, 0
	s_add_u32 s98, s98, 0x5780000
	s_addc_u32 s99, s99, 0
	s_waitcnt vmcnt(32)
	ds_write_b32 v4, v16
	ds_write_b32 v4, v17 offset:264
	ds_write_b32 v4, v18 offset:528
	ds_write_b32 v4, v19 offset:792
	ds_write_b32 v4, v20 offset:1056
	ds_write_b32 v4, v21 offset:1320
	ds_write_b32 v4, v22 offset:1584
	ds_write_b32 v4, v23 offset:1848
	ds_write_b32 v4, v24 offset:2112
	ds_write_b32 v4, v25 offset:2376
	ds_write_b32 v4, v26 offset:2640
	ds_write_b32 v4, v27 offset:2904
	ds_write_b32 v4, v28 offset:3168
	ds_write_b32 v4, v29 offset:3432
	ds_write_b32 v4, v30 offset:3696
	ds_write_b32 v4, v31 offset:3960
	ds_write_b32 v4, v32 offset:4224
	ds_write_b32 v4, v33 offset:4488
	ds_write_b32 v4, v34 offset:4752
	ds_write_b32 v4, v35 offset:5016
	ds_write_b32 v4, v36 offset:5280
	ds_write_b32 v4, v37 offset:5544
	ds_write_b32 v4, v38 offset:5808
	ds_write_b32 v4, v39 offset:6072
	ds_write_b32 v4, v40 offset:6336
	ds_write_b32 v4, v41 offset:6600
	ds_write_b32 v4, v42 offset:6864
	ds_write_b32 v4, v43 offset:7128
	ds_write_b32 v4, v44 offset:7392
	ds_write_b32 v4, v45 offset:7656
	ds_write_b32 v4, v46 offset:7920
	ds_write_b32 v4, v47 offset:8184
	s_waitcnt lgkmcnt(0)
	ds_read_b32 v48, v7
	ds_read_b32 v49, v7 offset:132
	ds_read_b32 v50, v7 offset:264
	ds_read_b32 v51, v7 offset:396
	ds_read_b32 v52, v7 offset:528
	ds_read_b32 v53, v7 offset:660
	ds_read_b32 v54, v7 offset:792
	ds_read_b32 v55, v7 offset:924
	s_waitcnt lgkmcnt(0)
	v_cvt_pk_bf16_f32 v80, v48, v49
	v_cvt_pk_bf16_f32 v81, v50, v51
	v_cvt_pk_bf16_f32 v82, v52, v53
	v_cvt_pk_bf16_f32 v83, v54, v55
	global_store_dwordx4 v8, v[80:83], s[100:101]
	ds_read_b32 v56, v7 offset:32
	ds_read_b32 v57, v7 offset:164
	ds_read_b32 v58, v7 offset:296
	ds_read_b32 v59, v7 offset:428
	ds_read_b32 v60, v7 offset:560
	ds_read_b32 v61, v7 offset:692
	ds_read_b32 v62, v7 offset:824
	ds_read_b32 v63, v7 offset:956
	s_waitcnt lgkmcnt(0)
	v_cvt_pk_bf16_f32 v84, v56, v57
	v_cvt_pk_bf16_f32 v85, v58, v59
	v_cvt_pk_bf16_f32 v86, v60, v61
	v_cvt_pk_bf16_f32 v87, v62, v63
	global_store_dwordx4 v9, v[84:87], s[100:101]
	ds_read_b32 v64, v7 offset:64
	ds_read_b32 v65, v7 offset:196
	ds_read_b32 v66, v7 offset:328
	ds_read_b32 v67, v7 offset:460
	ds_read_b32 v68, v7 offset:592
	ds_read_b32 v69, v7 offset:724
	ds_read_b32 v70, v7 offset:856
	ds_read_b32 v71, v7 offset:988
	s_waitcnt lgkmcnt(0)
	v_cvt_pk_bf16_f32 v88, v64, v65
	v_cvt_pk_bf16_f32 v89, v66, v67
	v_cvt_pk_bf16_f32 v90, v68, v69
	v_cvt_pk_bf16_f32 v91, v70, v71
	global_store_dwordx4 v10, v[88:91], s[100:101]
	ds_read_b32 v72, v7 offset:96
	ds_read_b32 v73, v7 offset:228
	ds_read_b32 v74, v7 offset:360
	ds_read_b32 v75, v7 offset:492
	ds_read_b32 v76, v7 offset:624
	ds_read_b32 v77, v7 offset:756
	ds_read_b32 v78, v7 offset:888
	ds_read_b32 v79, v7 offset:1020
	s_waitcnt lgkmcnt(0)
	v_cvt_pk_bf16_f32 v92, v72, v73
	v_cvt_pk_bf16_f32 v93, v74, v75
	v_cvt_pk_bf16_f32 v94, v76, v77
	v_cvt_pk_bf16_f32 v95, v78, v79
	global_store_dwordx4 v11, v[92:95], s[100:101]
	s_add_i32 s85, s85, 0x280
	s_cmp_lt_u32 s85, 0x800
	s_cbranch_scc0 .Lp7t_pleg_lastB
; #define LAS __attribute__((address_space(3)))
; __device__ __forceinline__ unsigned pk2(float lo, float hi) { const f32x2_t v = {lo, hi}; const bf16x2_t b = __builtin_convertvector(v, bf16x2_t); return __builtin_bit_cast(unsigned, b); }
; #define LDS_WAIT() asm volatile("s_waitcnt lgkmcnt(0)" ::: "memory")
; __device__ __forceinline__ void transpose_item(const float* W, int N, int K, bf16_t* WT, int k0, int n0src, int n0dst, LAS float* scr, int lane) {
;     float tv[32];
; #pragma unroll
;     for (int i = 0; i < 32; ++i) tv[i] = __builtin_nontemporal_load(&W[(size_t)(k0 + 2 * i + (lane >> 5)) * N + n0src + (lane & 31)]);
; #pragma unroll
;     for (int i = 0; i < 32; ++i) scr[(2 * i + (lane >> 5)) * 33 + (lane & 31)] = tv[i];
;     LDS_WAIT();
;     const int c = lane & 7;
; #pragma unroll
;     for (int j = 0; j < 4; ++j) { const int n = (lane >> 3) + 8 * j; const LAS float* s = scr + (8 * c) * 33 + n;
;         u32x4 o; o.x = pk2(s[0 * 33], s[1 * 33]); o.y = pk2(s[2 * 33], s[3 * 33]); o.z = pk2(s[4 * 33], s[5 * 33]); o.w = pk2(s[6 * 33], s[7 * 33]);
;         *(u32x4*)(WT + (size_t)(n0dst + n) * K + k0 + 8 * c) = o; }
;     LDS_WAIT();
; }
	s_lshr_b32 s91, s85, 6
	s_mul_i32 s92, s91, 0x40
	s_sub_i32 s92, s85, s92
	s_lshl_b32 s92, s92, 5
	s_mov_b32 s95, s92
	s_mul_i32 s96, s91, 0x80000
	s_lshl_b32 s97, s92, 2
	s_add_i32 s96, s96, s97
	s_add_u32 s96, s86, s96
	s_addc_u32 s97, s87, 0
	global_load_dword v16, v3, s[96:97] nt
	s_add_u32 s96, s96, 0x4000
	s_addc_u32 s97, s97, 0
	global_load_dword v17, v3, s[96:97] nt
	s_add_u32 s96, s96, 0x4000
	s_addc_u32 s97, s97, 0
	global_load_dword v18, v3, s[96:97] nt
	s_add_u32 s96, s96, 0x4000
	s_addc_u32 s97, s97, 0
	global_load_dword v19, v3, s[96:97] nt
	s_add_u32 s96, s96, 0x4000
	s_addc_u32 s97, s97, 0
	global_load_dword v20, v3, s[96:97] nt
	s_add_u32 s96, s96, 0x4000
	s_addc_u32 s97, s97, 0
	global_load_dword v21, v3, s[96:97] nt
	s_add_u32 s96, s96, 0x4000
	s_addc_u32 s97, s97, 0
	global_load_dword v22, v3, s[96:97] nt
	s_add_u32 s96, s96, 0x4000
	s_addc_u32 s97, s97, 0
	global_load_dword v23, v3, s[96:97] nt
	s_add_u32 s96, s96, 0x4000
	s_addc_u32 s97, s97, 0
	global_load_dword v24, v3, s[96:97] nt
	s_add_u32 s96, s96, 0x4000
	s_addc_u32 s97, s97, 0
	global_load_dword v25, v3, s[96:97] nt
	s_add_u32 s96, s96, 0x4000
	s_addc_u32 s97, s97, 0
	global_load_dword v26, v3, s[96:97] nt
	s_add_u32 s96, s96, 0x4000
	s_addc_u32 s97, s97, 0
	global_load_dword v27, v3, s[96:97] nt
	s_add_u32 s96, s96, 0x4000
	s_addc_u32 s97, s97, 0
	global_load_dword v28, v3, s[96:97] nt
	s_add_u32 s96, s96, 0x4000
	s_addc_u32 s97, s97, 0
	global_load_dword v29, v3, s[96:97] nt
	s_add_u32 s96, s96, 0x4000
	s_addc_u32 s97, s97, 0
	global_load_dword v30, v3, s[96:97] nt
	s_add_u32 s96, s96, 0x4000
	s_addc_u32 s97, s97, 0
	global_load_dword v31, v3, s[96:97] nt
	s_add_u32 s96, s96, 0x4000
	s_addc_u32 s97, s97, 0
	global_load_dword v32, v3, s[96:97] nt
	s_add_u32 s96, s96, 0x4000
	s_addc_u32 s97, s97, 0
	global_load_dword v33, v3, s[96:97] nt
	s_add_u32 s96, s96, 0x4000
	s_addc_u32 s97, s97, 0
	global_load_dword v34, v3, s[96:97] nt
	s_add_u32 s96, s96, 0x4000
	s_addc_u32 s97, s97, 0
	global_load_dword v35, v3, s[96:97] nt
	s_add_u32 s96, s96, 0x4000
	s_addc_u32 s97, s97, 0
	global_load_dword v36, v3, s[96:97] nt
	s_add_u32 s96, s96, 0x4000
	s_addc_u32 s97, s97, 0
	global_load_dword v37, v3, s[96:97] nt
	s_add_u32 s96, s96, 0x4000
	s_addc_u32 s97, s97, 0
	global_load_dword v38, v3, s[96:97] nt
	s_add_u32 s96, s96, 0x4000
	s_addc_u32 s97, s97, 0
	global_load_dword v39, v3, s[96:97] nt
	s_add_u32 s96, s96, 0x4000
	s_addc_u32 s97, s97, 0
	global_load_dword v40, v3, s[96:97] nt
	s_add_u32 s96, s96, 0x4000
	s_addc_u32 s97, s97, 0
	global_load_dword v41, v3, s[96:97] nt
	s_add_u32 s96, s96, 0x4000
	s_addc_u32 s97, s97, 0
	global_load_dword v42, v3, s[96:97] nt
	s_add_u32 s96, s96, 0x4000
	s_addc_u32 s97, s97, 0
	global_load_dword v43, v3, s[96:97] nt
	s_add_u32 s96, s96, 0x4000
	s_addc_u32 s97, s97, 0
	global_load_dword v44, v3, s[96:97] nt
	s_add_u32 s96, s96, 0x4000
	s_addc_u32 s97, s97, 0
	global_load_dword v45, v3, s[96:97] nt
	s_add_u32 s96, s96, 0x4000
	s_addc_u32 s97, s97, 0
	global_load_dword v46, v3, s[96:97] nt
	s_add_u32 s96, s96, 0x4000
	s_addc_u32 s97, s97, 0
	global_load_dword v47, v3, s[96:97] nt
	s_mul_i32 s92, s95, 0x1000
	s_lshl_b32 s93, s91, 7
	s_add_i32 s92, s92, s93
	s_add_u32 s100, s22, s92
	s_addc_u32 s101, s23, 0
	s_add_u32 s100, s100, 0x5780000
	s_addc_u32 s101, s101, 0
	s_waitcnt vmcnt(32)
	ds_write_b32 v4, v96
	ds_write_b32 v4, v97 offset:264
	ds_write_b32 v4, v98 offset:528
	ds_write_b32 v4, v99 offset:792
	ds_write_b32 v4, v100 offset:1056
	ds_write_b32 v4, v101 offset:1320
	ds_write_b32 v4, v102 offset:1584
	ds_write_b32 v4, v103 offset:1848
	ds_write_b32 v4, v104 offset:2112
	ds_write_b32 v4, v105 offset:2376
	ds_write_b32 v4, v106 offset:2640
	ds_write_b32 v4, v107 offset:2904
	ds_write_b32 v4, v108 offset:3168
	ds_write_b32 v4, v109 offset:3432
	ds_write_b32 v4, v110 offset:3696
	ds_write_b32 v4, v111 offset:3960
	ds_write_b32 v4, v112 offset:4224
	ds_write_b32 v4, v113 offset:4488
	ds_write_b32 v4, v114 offset:4752
	ds_write_b32 v4, v115 offset:5016
	ds_write_b32 v4, v116 offset:5280
	ds_write_b32 v4, v117 offset:5544
	ds_write_b32 v4, v118 offset:5808
	ds_write_b32 v4, v119 offset:6072
	ds_write_b32 v4, v120 offset:6336
	ds_write_b32 v4, v121 offset:6600
	ds_write_b32 v4, v122 offset:6864
	ds_write_b32 v4, v123 offset:7128
	ds_write_b32 v4, v124 offset:7392
	ds_write_b32 v4, v125 offset:7656
	ds_write_b32 v4, v126 offset:7920
	ds_write_b32 v4, v127 offset:8184
	s_waitcnt lgkmcnt(0)
	ds_read_b32 v48, v7
	ds_read_b32 v49, v7 offset:132
	ds_read_b32 v50, v7 offset:264
	ds_read_b32 v51, v7 offset:396
	ds_read_b32 v52, v7 offset:528
	ds_read_b32 v53, v7 offset:660
	ds_read_b32 v54, v7 offset:792
	ds_read_b32 v55, v7 offset:924
	s_waitcnt lgkmcnt(0)
	v_cvt_pk_bf16_f32 v80, v48, v49
	v_cvt_pk_bf16_f32 v81, v50, v51
	v_cvt_pk_bf16_f32 v82, v52, v53
	v_cvt_pk_bf16_f32 v83, v54, v55
	global_store_dwordx4 v8, v[80:83], s[98:99]
	ds_read_b32 v56, v7 offset:32
	ds_read_b32 v57, v7 offset:164
	ds_read_b32 v58, v7 offset:296
	ds_read_b32 v59, v7 offset:428
	ds_read_b32 v60, v7 offset:560
	ds_read_b32 v61, v7 offset:692
	ds_read_b32 v62, v7 offset:824
	ds_read_b32 v63, v7 offset:956
	s_waitcnt lgkmcnt(0)
	v_cvt_pk_bf16_f32 v84, v56, v57
	v_cvt_pk_bf16_f32 v85, v58, v59
	v_cvt_pk_bf16_f32 v86, v60, v61
	v_cvt_pk_bf16_f32 v87, v62, v63
	global_store_dwordx4 v9, v[84:87], s[98:99]
	ds_read_b32 v64, v7 offset:64
	ds_read_b32 v65, v7 offset:196
	ds_read_b32 v66, v7 offset:328
	ds_read_b32 v67, v7 offset:460
	ds_read_b32 v68, v7 offset:592
	ds_read_b32 v69, v7 offset:724
	ds_read_b32 v70, v7 offset:856
	ds_read_b32 v71, v7 offset:988
	s_waitcnt lgkmcnt(0)
	v_cvt_pk_bf16_f32 v88, v64, v65
	v_cvt_pk_bf16_f32 v89, v66, v67
	v_cvt_pk_bf16_f32 v90, v68, v69
	v_cvt_pk_bf16_f32 v91, v70, v71
	global_store_dwordx4 v10, v[88:91], s[98:99]
	ds_read_b32 v72, v7 offset:96
	ds_read_b32 v73, v7 offset:228
	ds_read_b32 v74, v7 offset:360
	ds_read_b32 v75, v7 offset:492
	ds_read_b32 v76, v7 offset:624
	ds_read_b32 v77, v7 offset:756
	ds_read_b32 v78, v7 offset:888
	ds_read_b32 v79, v7 offset:1020
	s_waitcnt lgkmcnt(0)
	v_cvt_pk_bf16_f32 v92, v72, v73
	v_cvt_pk_bf16_f32 v93, v74, v75
	v_cvt_pk_bf16_f32 v94, v76, v77
	v_cvt_pk_bf16_f32 v95, v78, v79
	global_store_dwordx4 v11, v[92:95], s[98:99]
	s_branch .Lp7t_pleg_loop
; #define LAS __attribute__((address_space(3)))
; __device__ __forceinline__ unsigned pk2(float lo, float hi) { const f32x2_t v = {lo, hi}; const bf16x2_t b = __builtin_convertvector(v, bf16x2_t); return __builtin_bit_cast(unsigned, b); }
; #define LDS_WAIT() asm volatile("s_waitcnt lgkmcnt(0)" ::: "memory")
; __device__ __forceinline__ void transpose_item(const float* W, int N, int K, bf16_t* WT, int k0, int n0src, int n0dst, LAS float* scr, int lane) {
;     float tv[32];
; #pragma unroll
;     for (int i = 0; i < 32; ++i) tv[i] = __builtin_nontemporal_load(&W[(size_t)(k0 + 2 * i + (lane >> 5)) * N + n0src + (lane & 31)]);
; #pragma unroll
;     for (int i = 0; i < 32; ++i) scr[(2 * i + (lane >> 5)) * 33 + (lane & 31)] = tv[i];
;     LDS_WAIT();
;     const int c = lane & 7;
; #pragma unroll
;     for (int j = 0; j < 4; ++j) { const int n = (lane >> 3) + 8 * j; const LAS float* s = scr + (8 * c) * 33 + n;
;         u32x4 o; o.x = pk2(s[0 * 33], s[1 * 33]); o.y = pk2(s[2 * 33], s[3 * 33]); o.z = pk2(s[4 * 33], s[5 * 33]); o.w = pk2(s[6 * 33], s[7 * 33]);
;         *(u32x4*)(WT + (size_t)(n0dst + n) * K + k0 + 8 * c) = o; }
;     LDS_WAIT();
; }
.Lp7t_pleg_lastA:
	s_waitcnt vmcnt(0)
	ds_write_b32 v4, v16
	ds_write_b32 v4, v17 offset:264
	ds_write_b32 v4, v18 offset:528
	ds_write_b32 v4, v19 offset:792
	ds_write_b32 v4, v20 offset:1056
	ds_write_b32 v4, v21 offset:1320
	ds_write_b32 v4, v22 offset:1584
	ds_write_b32 v4, v23 offset:1848
	ds_write_b32 v4, v24 offset:2112
	ds_write_b32 v4, v25 offset:2376
	ds_write_b32 v4, v26 offset:2640
	ds_write_b32 v4, v27 offset:2904
	ds_write_b32 v4, v28 offset:3168
	ds_write_b32 v4, v29 offset:3432
	ds_write_b32 v4, v30 offset:3696
	ds_write_b32 v4, v31 offset:3960
	ds_write_b32 v4, v32 offset:4224
	ds_write_b32 v4, v33 offset:4488
	ds_write_b32 v4, v34 offset:4752
	ds_write_b32 v4, v35 offset:5016
	ds_write_b32 v4, v36 offset:5280
	ds_write_b32 v4, v37 offset:5544
	ds_write_b32 v4, v38 offset:5808
	ds_write_b32 v4, v39 offset:6072
	ds_write_b32 v4, v40 offset:6336
	ds_write_b32 v4, v41 offset:6600
	ds_write_b32 v4, v42 offset:6864
	ds_write_b32 v4, v43 offset:7128
	ds_write_b32 v4, v44 offset:7392
	ds_write_b32 v4, v45 offset:7656
	ds_write_b32 v4, v46 offset:7920
	ds_write_b32 v4, v47 offset:8184
	s_waitcnt lgkmcnt(0)
	ds_read_b32 v48, v7
	ds_read_b32 v49, v7 offset:132
	ds_read_b32 v50, v7 offset:264
	ds_read_b32 v51, v7 offset:396
	ds_read_b32 v52, v7 offset:528
	ds_read_b32 v53, v7 offset:660
	ds_read_b32 v54, v7 offset:792
	ds_read_b32 v55, v7 offset:924
	s_waitcnt lgkmcnt(0)
	v_cvt_pk_bf16_f32 v80, v48, v49
	v_cvt_pk_bf16_f32 v81, v50, v51
	v_cvt_pk_bf16_f32 v82, v52, v53
	v_cvt_pk_bf16_f32 v83, v54, v55
	global_store_dwordx4 v8, v[80:83], s[100:101]
	ds_read_b32 v56, v7 offset:32
	ds_read_b32 v57, v7 offset:164
	ds_read_b32 v58, v7 offset:296
	ds_read_b32 v59, v7 offset:428
	ds_read_b32 v60, v7 offset:560
	ds_read_b32 v61, v7 offset:692
	ds_read_b32 v62, v7 offset:824
	ds_read_b32 v63, v7 offset:956
	s_waitcnt lgkmcnt(0)
	v_cvt_pk_bf16_f32 v84, v56, v57
	v_cvt_pk_bf16_f32 v85, v58, v59
	v_cvt_pk_bf16_f32 v86, v60, v61
	v_cvt_pk_bf16_f32 v87, v62, v63
	global_store_dwordx4 v9, v[84:87], s[100:101]
	ds_read_b32 v64, v7 offset:64
	ds_read_b32 v65, v7 offset:196
	ds_read_b32 v66, v7 offset:328
	ds_read_b32 v67, v7 offset:460
	ds_read_b32 v68, v7 offset:592
	ds_read_b32 v69, v7 offset:724
	ds_read_b32 v70, v7 offset:856
	ds_read_b32 v71, v7 offset:988
	s_waitcnt lgkmcnt(0)
	v_cvt_pk_bf16_f32 v88, v64, v65
	v_cvt_pk_bf16_f32 v89, v66, v67
	v_cvt_pk_bf16_f32 v90, v68, v69
	v_cvt_pk_bf16_f32 v91, v70, v71
	global_store_dwordx4 v10, v[88:91], s[100:101]
	ds_read_b32 v72, v7 offset:96
	ds_read_b32 v73, v7 offset:228
	ds_read_b32 v74, v7 offset:360
	ds_read_b32 v75, v7 offset:492
	ds_read_b32 v76, v7 offset:624
	ds_read_b32 v77, v7 offset:756
	ds_read_b32 v78, v7 offset:888
	ds_read_b32 v79, v7 offset:1020
	s_waitcnt lgkmcnt(0)
	v_cvt_pk_bf16_f32 v92, v72, v73
	v_cvt_pk_bf16_f32 v93, v74, v75
	v_cvt_pk_bf16_f32 v94, v76, v77
	v_cvt_pk_bf16_f32 v95, v78, v79
	global_store_dwordx4 v11, v[92:95], s[100:101]
	s_branch .Lp7t_pleg_done
; #define LAS __attribute__((address_space(3)))
; __device__ __forceinline__ unsigned pk2(float lo, float hi) { const f32x2_t v = {lo, hi}; const bf16x2_t b = __builtin_convertvector(v, bf16x2_t); return __builtin_bit_cast(unsigned, b); }
; #define LDS_WAIT() asm volatile("s_waitcnt lgkmcnt(0)" ::: "memory")
; __device__ __forceinline__ unsigned xb_ld(unsigned* p)              { return __hip_atomic_load(p, __ATOMIC_RELAXED, __HIP_MEMORY_SCOPE_AGENT); }
; __device__ __forceinline__ unsigned xb_xcc_id() { return (unsigned)__builtin_amdgcn_s_getreg((3 << 11) | 20) & 0xFu; }
; __device__ __forceinline__ void transpose_item(const float* W, int N, int K, bf16_t* WT, int k0, int n0src, int n0dst, LAS float* scr, int lane) {
;     float tv[32];
; #pragma unroll
;     for (int i = 0; i < 32; ++i) tv[i] = __builtin_nontemporal_load(&W[(size_t)(k0 + 2 * i + (lane >> 5)) * N + n0src + (lane & 31)]);
; #pragma unroll
;     for (int i = 0; i < 32; ++i) scr[(2 * i + (lane >> 5)) * 33 + (lane & 31)] = tv[i];
;     LDS_WAIT();
;     const int c = lane & 7;
; #pragma unroll
;     for (int j = 0; j < 4; ++j) { const int n = (lane >> 3) + 8 * j; const LAS float* s = scr + (8 * c) * 33 + n;
;         u32x4 o; o.x = pk2(s[0 * 33], s[1 * 33]); o.y = pk2(s[2 * 33], s[3 * 33]); o.z = pk2(s[4 * 33], s[5 * 33]); o.w = pk2(s[6 * 33], s[7 * 33]);
;         *(u32x4*)(WT + (size_t)(n0dst + n) * K + k0 + 8 * c) = o; }
;     LDS_WAIT();
; }
; __device__ __forceinline__ void xcd_barrier(unsigned* bar, volatile LAS unsigned* st, int wave_s) {
;     asm volatile("s_waitcnt vmcnt(0)" ::: "memory");
;     __syncthreads();
;     if (opaque_tid(wave_s) == 0) {
;         __builtin_amdgcn_s_waitcnt(0);
;         const unsigned x = xb_xcc_id();
;         unsigned nloc = st[0], nx = st[1];
;         if (nloc == 0u) {
;             const unsigned G = gridDim.x; unsigned sum, cnt, mine;
;             for (;;) { sum = 0u; cnt = 0u; mine = 0u;
; #pragma unroll
;                 for (unsigned j = 0; j < 16; ++j) { const unsigned c = xb_ld(&bar[XB_XCNT(j)]); sum += c; cnt += (c > 0u) ? 1u : 0u; mine = (j == x) ? c : mine; }
;                 if (sum == G) break;
;                 __builtin_amdgcn_s_sleep(1); }
;             nloc = mine > 0u ? mine : 1u; nx = cnt > 0u ? cnt : 1u; st[0] = nloc; st[1] = nx; }
.Lp7t_pleg_lastB:
	s_waitcnt vmcnt(0)
	ds_write_b32 v4, v96
	ds_write_b32 v4, v97 offset:264
	ds_write_b32 v4, v98 offset:528
	ds_write_b32 v4, v99 offset:792
	ds_write_b32 v4, v100 offset:1056
	ds_write_b32 v4, v101 offset:1320
	ds_write_b32 v4, v102 offset:1584
	ds_write_b32 v4, v103 offset:1848
	ds_write_b32 v4, v104 offset:2112
	ds_write_b32 v4, v105 offset:2376
	ds_write_b32 v4, v106 offset:2640
	ds_write_b32 v4, v107 offset:2904
	ds_write_b32 v4, v108 offset:3168
	ds_write_b32 v4, v109 offset:3432
	ds_write_b32 v4, v110 offset:3696
	ds_write_b32 v4, v111 offset:3960
	ds_write_b32 v4, v112 offset:4224
	ds_write_b32 v4, v113 offset:4488
	ds_write_b32 v4, v114 offset:4752
	ds_write_b32 v4, v115 offset:5016
	ds_write_b32 v4, v116 offset:5280
	ds_write_b32 v4, v117 offset:5544
	ds_write_b32 v4, v118 offset:5808
	ds_write_b32 v4, v119 offset:6072
	ds_write_b32 v4, v120 offset:6336
	ds_write_b32 v4, v121 offset:6600
	ds_write_b32 v4, v122 offset:6864
	ds_write_b32 v4, v123 offset:7128
	ds_write_b32 v4, v124 offset:7392
	ds_write_b32 v4, v125 offset:7656
	ds_write_b32 v4, v126 offset:7920
	ds_write_b32 v4, v127 offset:8184
	s_waitcnt lgkmcnt(0)
	ds_read_b32 v48, v7
	ds_read_b32 v49, v7 offset:132
	ds_read_b32 v50, v7 offset:264
	ds_read_b32 v51, v7 offset:396
	ds_read_b32 v52, v7 offset:528
	ds_read_b32 v53, v7 offset:660
	ds_read_b32 v54, v7 offset:792
	ds_read_b32 v55, v7 offset:924
	s_waitcnt lgkmcnt(0)
	v_cvt_pk_bf16_f32 v80, v48, v49
	v_cvt_pk_bf16_f32 v81, v50, v51
	v_cvt_pk_bf16_f32 v82, v52, v53
	v_cvt_pk_bf16_f32 v83, v54, v55
	global_store_dwordx4 v8, v[80:83], s[98:99]
	ds_read_b32 v56, v7 offset:32
	ds_read_b32 v57, v7 offset:164
	ds_read_b32 v58, v7 offset:296
	ds_read_b32 v59, v7 offset:428
	ds_read_b32 v60, v7 offset:560
	ds_read_b32 v61, v7 offset:692
	ds_read_b32 v62, v7 offset:824
	ds_read_b32 v63, v7 offset:956
	s_waitcnt lgkmcnt(0)
	v_cvt_pk_bf16_f32 v84, v56, v57
	v_cvt_pk_bf16_f32 v85, v58, v59
	v_cvt_pk_bf16_f32 v86, v60, v61
	v_cvt_pk_bf16_f32 v87, v62, v63
	global_store_dwordx4 v9, v[84:87], s[98:99]
	ds_read_b32 v64, v7 offset:64
	ds_read_b32 v65, v7 offset:196
	ds_read_b32 v66, v7 offset:328
	ds_read_b32 v67, v7 offset:460
	ds_read_b32 v68, v7 offset:592
	ds_read_b32 v69, v7 offset:724
	ds_read_b32 v70, v7 offset:856
	ds_read_b32 v71, v7 offset:988
	s_waitcnt lgkmcnt(0)
	v_cvt_pk_bf16_f32 v88, v64, v65
	v_cvt_pk_bf16_f32 v89, v66, v67
	v_cvt_pk_bf16_f32 v90, v68, v69
	v_cvt_pk_bf16_f32 v91, v70, v71
	global_store_dwordx4 v10, v[88:91], s[98:99]
	ds_read_b32 v72, v7 offset:96
	ds_read_b32 v73, v7 offset:228
	ds_read_b32 v74, v7 offset:360
	ds_read_b32 v75, v7 offset:492
	ds_read_b32 v76, v7 offset:624
	ds_read_b32 v77, v7 offset:756
	ds_read_b32 v78, v7 offset:888
	ds_read_b32 v79, v7 offset:1020
	s_waitcnt lgkmcnt(0)
	v_cvt_pk_bf16_f32 v92, v72, v73
	v_cvt_pk_bf16_f32 v93, v74, v75
	v_cvt_pk_bf16_f32 v94, v76, v77
	v_cvt_pk_bf16_f32 v95, v78, v79
	global_store_dwordx4 v11, v[92:95], s[98:99]
.Lp7t_pleg_done:
.Lp9a_skip:
.LBB0_1235:
	s_cmp_gt_i32 s19, 8
	s_cselect_b64 s[0:1], -1, 0
	s_and_b64 s[4:5], s[4:5], s[0:1]
	s_andn2_b64 vcc, exec, s[4:5]
	s_cbranch_vccnz .LBB0_1266
	s_waitcnt vmcnt(0)
	s_waitcnt vmcnt(0)
	s_barrier
	s_mov_b32 s3, 0
	s_nop 0
	v_mbcnt_lo_u32_b32 v0, -1, s3
	v_mbcnt_hi_u32_b32 v0, -1, v0
	v_or_b32_e32 v0, s24, v0
	s_nop 0
	v_cmp_eq_u32_e32 vcc, 0, v0
	s_and_saveexec_b64 s[4:5], vcc
	s_cbranch_execz .LBB0_1265
	s_add_i32 s6, 0, 0x23ff0
	v_mov_b32_e32 v0, s6
	s_waitcnt vmcnt(0) expcnt(0) lgkmcnt(0)
	s_getreg_b32 s3, hwreg(HW_REG_XCC_ID, 0, 4)
	ds_read_b32 v1, v0
	s_add_i32 s6, 0, 0x23ff4
	v_mov_b32_e32 v0, s6
	ds_read_b32 v0, v0
	s_and_b32 s3, s3, 15
	s_waitcnt lgkmcnt(1)
	v_cmp_ne_u32_e32 vcc, 0, v1
	s_cbranch_vccnz .LBB0_1243
	s_add_u32 s6, s22, 0x1f32a400
	s_addc_u32 s7, s23, 0
	s_add_u32 s8, s22, 0x1f32a500
	s_addc_u32 s9, s23, 0
	s_add_u32 s10, s22, 0x1f32a600
	s_addc_u32 s11, s23, 0
	s_add_u32 s12, s22, 0x1f32a700
	s_addc_u32 s13, s23, 0
	s_add_u32 s14, s22, 0x1f32a800
	s_addc_u32 s15, s23, 0
	s_add_u32 s16, s22, 0x1f32a900
	s_addc_u32 s17, s23, 0
	s_add_u32 s26, s22, 0x1f32aa00
	s_addc_u32 s27, s23, 0
	s_add_u32 s28, s22, 0x1f32ab00
	s_addc_u32 s29, s23, 0
	s_add_u32 s30, s22, 0x1f32ac00
	s_addc_u32 s31, s23, 0
	s_add_u32 s34, s22, 0x1f32ad00
	s_addc_u32 s35, s23, 0
	s_add_u32 s36, s22, 0x1f32ae00
	s_addc_u32 s37, s23, 0
	s_add_u32 s38, s22, 0x1f32af00
	s_addc_u32 s39, s23, 0
	s_add_u32 s40, s22, 0x1f32b000
	s_addc_u32 s41, s23, 0
	s_add_u32 s42, s22, 0x1f32b100
	s_addc_u32 s43, s23, 0
	s_add_u32 s44, s22, 0x1f32b200
	s_addc_u32 s45, s23, 0
	s_add_u32 s46, s22, 0x1f32b300
	s_addc_u32 s47, s23, 0
	v_mov_b32_e32 v16, 0
	s_branch .LBB0_1240

; __global__ void __launch_bounds__(512, 2) mega(Params p) {
	.amdhsa_kernel _Z4mega6Params
		.amdhsa_group_segment_fixed_size 0
		.amdhsa_private_segment_fixed_size 0
		.amdhsa_kernarg_size 472
		.amdhsa_user_sgpr_count 2
		.amdhsa_user_sgpr_dispatch_ptr 0
		.amdhsa_user_sgpr_queue_ptr 0
		.amdhsa_user_sgpr_kernarg_segment_ptr 1
		.amdhsa_user_sgpr_dispatch_id 0
		.amdhsa_user_sgpr_kernarg_preload_length 0
		.amdhsa_user_sgpr_kernarg_preload_offset 0
		.amdhsa_user_sgpr_private_segment_size 0
		.amdhsa_uses_dynamic_stack 0
		.amdhsa_enable_private_segment 0
		.amdhsa_system_sgpr_workgroup_id_x 1
		.amdhsa_system_sgpr_workgroup_id_y 0
		.amdhsa_system_sgpr_workgroup_id_z 0
		.amdhsa_system_sgpr_workgroup_info 0
		.amdhsa_system_vgpr_workitem_id 2
		.amdhsa_next_free_vgpr 255
		.amdhsa_next_free_sgpr 102
		.amdhsa_accum_offset 256
		.amdhsa_reserve_vcc 1
		.amdhsa_float_round_mode_32 0
		.amdhsa_float_round_mode_16_64 0
		.amdhsa_float_denorm_mode_32 3
		.amdhsa_float_denorm_mode_16_64 3
		.amdhsa_dx10_clamp 1
		.amdhsa_ieee_mode 1
		.amdhsa_fp16_overflow 0
		.amdhsa_tg_split 0
		.amdhsa_exception_fp_ieee_invalid_op 0
		.amdhsa_exception_fp_denorm_src 0
		.amdhsa_exception_fp_ieee_div_zero 0
		.amdhsa_exception_fp_ieee_overflow 0
		.amdhsa_exception_fp_ieee_underflow 0
		.amdhsa_exception_fp_ieee_inexact 0
		.amdhsa_exception_int_div_zero 0
	.end_amdhsa_kernel

; __global__ void __launch_bounds__(512, 2) mega(Params p) {
amdhsa.kernels:
  - .agpr_count:     0
    .args:
      - .offset:         0
        .size:           216
        .value_kind:     by_value
      - .offset:         216
        .size:           4
        .value_kind:     hidden_block_count_x
      - .offset:         220
        .size:           4
        .value_kind:     hidden_block_count_y
      - .offset:         224
        .size:           4
        .value_kind:     hidden_block_count_z
      - .offset:         228
        .size:           2
        .value_kind:     hidden_group_size_x
      - .offset:         230
        .size:           2
        .value_kind:     hidden_group_size_y
      - .offset:         232
        .size:           2
        .value_kind:     hidden_group_size_z
      - .offset:         234
        .size:           2
        .value_kind:     hidden_remainder_x
      - .offset:         236
        .size:           2
        .value_kind:     hidden_remainder_y
      - .offset:         238
        .size:           2
        .value_kind:     hidden_remainder_z
      - .offset:         256
        .size:           8
        .value_kind:     hidden_global_offset_x
      - .offset:         264
        .size:           8
        .value_kind:     hidden_global_offset_y
      - .offset:         272
        .size:           8
        .value_kind:     hidden_global_offset_z
      - .offset:         280
        .size:           2
        .value_kind:     hidden_grid_dims
      - .offset:         304
        .size:           8
        .value_kind:     hidden_multigrid_sync_arg
      - .offset:         336
        .size:           4
        .value_kind:     hidden_dynamic_lds_size
    .group_segment_fixed_size: 0
    .kernarg_segment_align: 8
    .kernarg_segment_size: 472
    .language:       OpenCL C
    .language_version:
      - 2
      - 0
    .max_flat_workgroup_size: 512
    .name:           _Z4mega6Params
    .private_segment_fixed_size: 0
    .sgpr_count:     108
    .sgpr_spill_count: 22
    .symbol:         _Z4mega6Params.kd
    .uniform_work_group_size: 1
    .uses_dynamic_stack: false
    .vgpr_count:     255
    .vgpr_spill_count: 0
    .wavefront_size: 64
